# LN loops: dead copies into the next-row prefetch registers removed (66 v_mov over the four LN loops), on top of the router-logit rewrite
# baseline (speedup 1.0000x reference)
.LBB0_682:
	s_or_b64 exec, exec, s[16:17]
	v_add_u32_e32 v128, 4, v114
	v_cmp_gt_i32_e32 vcc, s0, v128
	v_cmp_le_i32_e64 s[16:17], s0, v128
	s_waitcnt vmcnt(0)
	s_and_saveexec_b64 s[24:25], vcc
	s_cbranch_execz .LBB0_684
	v_ashrrev_i32_e32 v129, 31, v128
	v_lshlrev_b64 v[80:81], 12, v[128:129]
	v_lshl_add_u64 v[92:93], v[118:119], 0, v[80:81]
	v_lshlrev_b64 v[80:81], 11, v[128:129]
	v_lshl_add_u64 v[130:131], v[120:121], 0, v[80:81]
	global_load_dwordx4 v[80:83], v[92:93], off nt
	global_load_dwordx4 v[84:87], v[92:93], off offset:1024 nt
	global_load_dwordx4 v[88:91], v[92:93], off offset:2048 nt
	s_nop 0
	global_load_dwordx4 v[92:95], v[92:93], off offset:3072 nt
	s_nop 0
	global_load_dwordx2 v[136:137], v[130:131], off
	global_load_dwordx2 v[134:135], v[130:131], off offset:512
	global_load_dwordx2 v[132:133], v[130:131], off offset:1024
	s_nop 0
	global_load_dwordx2 v[130:131], v[130:131], off offset:1536

.LBB0_1098:
	s_or_b64 exec, exec, s[8:9]
	v_add_u32_e32 v124, 4, v112
	v_cmp_gt_i32_e32 vcc, s2, v124
	v_cmp_le_i32_e64 s[8:9], s2, v124
	v_mov_b64_e32 v[130:131], v[126:127]
	v_mov_b64_e32 v[132:133], v[128:129]
	s_and_saveexec_b64 s[16:17], vcc
	s_cbranch_execz .LBB0_1102
	v_ashrrev_i32_e32 v125, 31, v124
	v_lshlrev_b64 v[96:97], 12, v[124:125]
	v_lshl_add_u64 v[104:105], v[116:117], 0, v[96:97]
	global_load_dwordx4 v[96:99], v[104:105], off nt
	global_load_dwordx4 v[100:103], v[104:105], off offset:1024 nt
	global_load_dwordx4 v[108:111], v[104:105], off offset:2048 nt
	s_nop 0
	global_load_dwordx4 v[104:107], v[104:105], off offset:3072 nt
	v_mov_b32_e32 v197, -1
	s_and_saveexec_b64 s[18:19], s[6:7]
	s_cbranch_execz .LBB0_1101
	v_lshlrev_b64 v[130:131], 6, v[124:125]
	v_lshl_add_u64 v[130:131], v[118:119], 0, v[130:131]
	global_load_dword v197, v[130:131], off

.LBB0_1397:
	s_or_b64 exec, exec, s[16:17]
	v_add_u32_e32 v128, 4, v114
	v_cmp_gt_i32_e32 vcc, s2, v128
	v_cmp_le_i32_e64 s[16:17], s2, v128
	s_waitcnt vmcnt(0)
	s_and_saveexec_b64 s[26:27], vcc
	s_cbranch_execz .LBB0_1399
	v_ashrrev_i32_e32 v129, 31, v128
	v_lshlrev_b64 v[80:81], 12, v[128:129]
	v_lshl_add_u64 v[92:93], v[118:119], 0, v[80:81]
	v_lshlrev_b64 v[80:81], 11, v[128:129]
	v_lshl_add_u64 v[130:131], v[120:121], 0, v[80:81]
	global_load_dwordx4 v[80:83], v[92:93], off nt
	global_load_dwordx4 v[84:87], v[92:93], off offset:1024 nt
	global_load_dwordx4 v[88:91], v[92:93], off offset:2048 nt
	s_nop 0
	global_load_dwordx4 v[92:95], v[92:93], off offset:3072 nt
	s_nop 0
	global_load_dwordx2 v[136:137], v[130:131], off
	global_load_dwordx2 v[134:135], v[130:131], off offset:512
	global_load_dwordx2 v[132:133], v[130:131], off offset:1024
	s_nop 0
	global_load_dwordx2 v[130:131], v[130:131], off offset:1536

.LBB0_1813:
	s_or_b64 exec, exec, s[6:7]
	v_add_u32_e32 v58, 4, v80
	v_cmp_gt_i32_e32 vcc, s0, v58
	v_cmp_le_i32_e64 s[6:7], s0, v58
	v_mov_b64_e32 v[92:93], v[96:97]
	v_mov_b64_e32 v[94:95], v[98:99]
	s_and_saveexec_b64 s[14:15], vcc
	s_cbranch_execz .LBB0_1817
	v_ashrrev_i32_e32 v59, 31, v58
	v_lshlrev_b64 v[64:65], 12, v[58:59]
	v_lshl_add_u64 v[92:93], v[84:85], 0, v[64:65]
	global_load_dwordx4 v[64:67], v[92:93], off nt
	global_load_dwordx4 v[68:71], v[92:93], off offset:1024 nt
	global_load_dwordx4 v[76:79], v[92:93], off offset:2048 nt
	global_load_dwordx4 v[72:75], v[92:93], off offset:3072 nt
	v_mov_b32_e32 v161, -1
	s_and_saveexec_b64 s[16:17], s[2:3]
	s_cbranch_execz .LBB0_1816
	v_lshlrev_b64 v[92:93], 6, v[58:59]
	v_lshl_add_u64 v[92:93], v[86:87], 0, v[92:93]
	global_load_dword v161, v[92:93], off
